# 64-byte alignment of the four big GEMM K-loop heads (code placement)
# baseline (speedup 1.0000x reference)
; template <class Epi, class Sched, bool ALIGN_EPI = true>
; __device__ __forceinline__ void gemm_phase(LAS unsigned char* lds, const Gemm g, const Sched& S, const Epi& E, const int tid) {
;     ...
;         const bool has_next = S.next(ui + 1, nxt);
;         const char* nA = has_next ? (const char*)g.A + (size_t)nxt.pm * tstepA + (size_t)nxt.koff * 2 : cA; const char* nB = has_next ? (const char*)g.Bt + (size_t)nxt.pn * tstepB + (size_t)nxt.koff * 2 : cB;
;         const int nt = cur.nt;
;         for (int t = 0; t < nt; t += 2) {
;             const bool last = (t == nt - 2);
;             const char* a1 = cA + (size_t)(t + 1) * kstep;
;             const char* a2 = last ? nA : cA + (size_t)(t + 2) * kstep; const char* b2 = last ? nB : cB + (size_t)(t + 2) * kstep;
;     ...
; #pragma unroll
;         for (int a = 0; a < 2; ++a)
; #pragma unroll
;             for (int b = 0; b < 2; ++b)
; #pragma unroll
;                 for (int m = 0; m < 4; ++m)
; #pragma unroll
;                     for (int n = 0; n < 2; ++n) acc[a][b][m][n] = (f32x4){0.f, 0.f, 0.f, 0.f};
.LBB0_168:
	s_ashr_i32 s11, s10, 31
	s_lshl_b64 s[12:13], s[10:11], 19
	s_add_u32 s9, s26, s12
	s_addc_u32 s11, s27, s13
	s_and_b64 s[12:13], s[16:17], exec
	s_cselect_b32 s13, s11, s21
	s_cselect_b32 s12, s9, s20
	s_ashr_i32 s9, s8, 31
	s_lshl_b64 s[14:15], s[8:9], 19
	s_add_u32 s9, s28, s14
	s_addc_u32 s11, s29, s15
	s_and_b64 s[14:15], s[16:17], exec
	s_cselect_b32 s15, s11, s23
	s_cselect_b32 s14, s9, s22
	s_add_u32 s20, s20, 0x40080
	s_addc_u32 s21, s21, 0
	s_add_u32 s9, s22, 0x100
	v_mov_b32_e32 v0, 0
	s_addc_u32 s11, s23, 0
	s_mov_b32 s47, -2
	v_add_u32_e32 v137, 0, v1
	v_mov_b32_e32 v1, v0
	v_mov_b32_e32 v2, v0
	v_mov_b32_e32 v3, v0
	v_mov_b32_e32 v4, v0
	v_mov_b32_e32 v5, v0
	v_mov_b32_e32 v6, v0
	v_mov_b32_e32 v7, v0
	v_mov_b32_e32 v8, v0
	v_mov_b32_e32 v9, v0
	v_mov_b32_e32 v10, v0
	v_mov_b32_e32 v11, v0
	v_mov_b32_e32 v16, v0
	v_mov_b32_e32 v17, v0
	v_mov_b32_e32 v18, v0
	v_mov_b32_e32 v19, v0
	v_mov_b32_e32 v24, v0
	v_mov_b32_e32 v25, v0
	v_mov_b32_e32 v26, v0
	v_mov_b32_e32 v27, v0
	v_mov_b32_e32 v32, v0
	v_mov_b32_e32 v33, v0
	v_mov_b32_e32 v34, v0
	v_mov_b32_e32 v35, v0
	v_mov_b32_e32 v40, v0
	v_mov_b32_e32 v41, v0
	v_mov_b32_e32 v42, v0
	v_mov_b32_e32 v43, v0
	v_mov_b32_e32 v48, v0
	v_mov_b32_e32 v49, v0
	v_mov_b32_e32 v50, v0
	v_mov_b32_e32 v51, v0
	v_mov_b32_e32 v12, v0
	v_mov_b32_e32 v13, v0
	v_mov_b32_e32 v14, v0
	v_mov_b32_e32 v15, v0
	v_mov_b32_e32 v20, v0
	v_mov_b32_e32 v21, v0
	v_mov_b32_e32 v22, v0
	v_mov_b32_e32 v23, v0
	v_mov_b32_e32 v28, v0
	v_mov_b32_e32 v29, v0
	v_mov_b32_e32 v30, v0
	v_mov_b32_e32 v31, v0
	v_mov_b32_e32 v36, v0
	v_mov_b32_e32 v37, v0
	v_mov_b32_e32 v38, v0
	v_mov_b32_e32 v39, v0
	v_mov_b32_e32 v44, v0
	v_mov_b32_e32 v45, v0
	v_mov_b32_e32 v46, v0
	v_mov_b32_e32 v47, v0
	v_mov_b32_e32 v52, v0
	v_mov_b32_e32 v53, v0
	v_mov_b32_e32 v54, v0
	v_mov_b32_e32 v55, v0
	v_mov_b32_e32 v56, v0
	v_mov_b32_e32 v57, v0
	v_mov_b32_e32 v58, v0
	v_mov_b32_e32 v59, v0
	v_mov_b32_e32 v60, v0
	v_mov_b32_e32 v61, v0
	v_mov_b32_e32 v62, v0
	v_mov_b32_e32 v63, v0
	v_mov_b32_e32 v64, v0
	v_mov_b32_e32 v65, v0
	v_mov_b32_e32 v66, v0
	v_mov_b32_e32 v67, v0
	v_mov_b32_e32 v68, v0
	v_mov_b32_e32 v69, v0
	v_mov_b32_e32 v70, v0
	v_mov_b32_e32 v71, v0
	v_mov_b32_e32 v72, v0
	v_mov_b32_e32 v73, v0
	v_mov_b32_e32 v74, v0
	v_mov_b32_e32 v75, v0
	v_mov_b32_e32 v80, v0
	v_mov_b32_e32 v81, v0
	v_mov_b32_e32 v82, v0
	v_mov_b32_e32 v83, v0
	v_mov_b32_e32 v88, v0
	v_mov_b32_e32 v89, v0
	v_mov_b32_e32 v90, v0
	v_mov_b32_e32 v91, v0
	v_mov_b32_e32 v96, v0
	v_mov_b32_e32 v97, v0
	v_mov_b32_e32 v98, v0
	v_mov_b32_e32 v99, v0
	v_mov_b32_e32 v104, v0
	v_mov_b32_e32 v105, v0
	v_mov_b32_e32 v106, v0
	v_mov_b32_e32 v107, v0
	v_mov_b32_e32 v112, v0
	v_mov_b32_e32 v113, v0
	v_mov_b32_e32 v114, v0
	v_mov_b32_e32 v115, v0
	v_mov_b32_e32 v76, v0
	v_mov_b32_e32 v77, v0
	v_mov_b32_e32 v78, v0
	v_mov_b32_e32 v79, v0
	v_mov_b32_e32 v84, v0
	v_mov_b32_e32 v85, v0
	v_mov_b32_e32 v86, v0
	v_mov_b32_e32 v87, v0
	v_mov_b32_e32 v92, v0
	v_mov_b32_e32 v93, v0
	v_mov_b32_e32 v94, v0
	v_mov_b32_e32 v95, v0
	v_mov_b32_e32 v100, v0
	v_mov_b32_e32 v101, v0
	v_mov_b32_e32 v102, v0
	v_mov_b32_e32 v103, v0
	v_mov_b32_e32 v108, v0
	v_mov_b32_e32 v109, v0
	v_mov_b32_e32 v110, v0
	v_mov_b32_e32 v111, v0
	v_mov_b32_e32 v116, v0
	v_mov_b32_e32 v117, v0
	v_mov_b32_e32 v118, v0
	v_mov_b32_e32 v119, v0
	v_mov_b32_e32 v120, v0
	v_mov_b32_e32 v121, v0
	v_mov_b32_e32 v122, v0
	v_mov_b32_e32 v123, v0
	v_mov_b32_e32 v124, v0
	v_mov_b32_e32 v125, v0
	v_mov_b32_e32 v126, v0
	v_mov_b32_e32 v127, v0
	v_mov_b32_e32 v133, v145
	v_mov_b32_e32 v129, v145
	v_mov_b32_e32 v131, v145
	.p2align	6

; template <class Epi, class Sched, bool ALIGN_EPI = true>
; __device__ __forceinline__ void gemm_phase(LAS unsigned char* lds, const Gemm g, const Sched& S, const Epi& E, const int tid) {
;     ...
;         const bool has_next = S.next(ui + 1, nxt);
;         const char* nA = has_next ? (const char*)g.A + (size_t)nxt.pm * tstepA + (size_t)nxt.koff * 2 : cA; const char* nB = has_next ? (const char*)g.Bt + (size_t)nxt.pn * tstepB + (size_t)nxt.koff * 2 : cB;
;         const int nt = cur.nt;
;         for (int t = 0; t < nt; t += 2) {
;             const bool last = (t == nt - 2);
;             const char* a1 = cA + (size_t)(t + 1) * kstep;
;             const char* a2 = last ? nA : cA + (size_t)(t + 2) * kstep; const char* b2 = last ? nB : cB + (size_t)(t + 2) * kstep;
;     ...
; #pragma unroll
;         for (int a = 0; a < 2; ++a)
; #pragma unroll
;             for (int b = 0; b < 2; ++b)
; #pragma unroll
;                 for (int m = 0; m < 4; ++m)
; #pragma unroll
;                     for (int n = 0; n < 2; ++n) acc[a][b][m][n] = (f32x4){0.f, 0.f, 0.f, 0.f};
.LBB0_684:
	s_ashr_i32 s17, s16, 31
	s_lshl_b64 s[18:19], s[16:17], 19
	s_add_u32 s15, s39, s18
	s_addc_u32 s17, s40, s19
	s_and_b64 s[18:19], s[22:23], exec
	s_cselect_b32 s19, s17, s29
	s_cselect_b32 s18, s15, s28
	s_ashr_i32 s15, s14, 31
	s_lshl_b64 s[20:21], s[14:15], 19
	s_add_u32 s15, s41, s20
	s_addc_u32 s17, s42, s21
	s_and_b64 s[20:21], s[22:23], exec
	s_cselect_b32 s21, s17, s31
	s_cselect_b32 s20, s15, s30
	s_add_u32 s28, s28, 0x40080
	s_addc_u32 s29, s29, 0
	s_add_u32 s15, s30, 0x100
	v_mov_b32_e32 v0, 0
	v_mov_b32_e32 v129, v145
	s_addc_u32 s17, s31, 0
	s_mov_b32 s36, -2
	v_add_u32_e32 v131, 0, v8
	v_mov_b32_e32 v1, v0
	v_mov_b32_e32 v2, v0
	v_mov_b32_e32 v3, v0
	v_mov_b32_e32 v4, v0
	v_mov_b32_e32 v5, v0
	v_mov_b32_e32 v6, v0
	v_mov_b32_e32 v7, v0
	v_mov_b32_e32 v8, v0
	v_mov_b32_e32 v9, v0
	v_mov_b32_e32 v10, v0
	v_mov_b32_e32 v11, v0
	v_mov_b32_e32 v16, v0
	v_mov_b32_e32 v17, v0
	v_mov_b32_e32 v18, v0
	v_mov_b32_e32 v19, v0
	v_mov_b32_e32 v24, v0
	v_mov_b32_e32 v25, v0
	v_mov_b32_e32 v26, v0
	v_mov_b32_e32 v27, v0
	v_mov_b32_e32 v32, v0
	v_mov_b32_e32 v33, v0
	v_mov_b32_e32 v34, v0
	v_mov_b32_e32 v35, v0
	v_mov_b32_e32 v40, v0
	v_mov_b32_e32 v41, v0
	v_mov_b32_e32 v42, v0
	v_mov_b32_e32 v43, v0
	v_mov_b32_e32 v48, v0
	v_mov_b32_e32 v49, v0
	v_mov_b32_e32 v50, v0
	v_mov_b32_e32 v51, v0
	v_mov_b32_e32 v12, v0
	v_mov_b32_e32 v13, v0
	v_mov_b32_e32 v14, v0
	v_mov_b32_e32 v15, v0
	v_mov_b32_e32 v20, v0
	v_mov_b32_e32 v21, v0
	v_mov_b32_e32 v22, v0
	v_mov_b32_e32 v23, v0
	v_mov_b32_e32 v28, v0
	v_mov_b32_e32 v29, v0
	v_mov_b32_e32 v30, v0
	v_mov_b32_e32 v31, v0
	v_mov_b32_e32 v36, v0
	v_mov_b32_e32 v37, v0
	v_mov_b32_e32 v38, v0
	v_mov_b32_e32 v39, v0
	v_mov_b32_e32 v44, v0
	v_mov_b32_e32 v45, v0
	v_mov_b32_e32 v46, v0
	v_mov_b32_e32 v47, v0
	v_mov_b32_e32 v52, v0
	v_mov_b32_e32 v53, v0
	v_mov_b32_e32 v54, v0
	v_mov_b32_e32 v55, v0
	v_mov_b32_e32 v56, v0
	v_mov_b32_e32 v57, v0
	v_mov_b32_e32 v58, v0
	v_mov_b32_e32 v59, v0
	v_mov_b32_e32 v60, v0
	v_mov_b32_e32 v61, v0
	v_mov_b32_e32 v62, v0
	v_mov_b32_e32 v63, v0
	v_mov_b32_e32 v64, v0
	v_mov_b32_e32 v65, v0
	v_mov_b32_e32 v66, v0
	v_mov_b32_e32 v67, v0
	v_mov_b32_e32 v68, v0
	v_mov_b32_e32 v69, v0
	v_mov_b32_e32 v70, v0
	v_mov_b32_e32 v71, v0
	v_mov_b32_e32 v72, v0
	v_mov_b32_e32 v73, v0
	v_mov_b32_e32 v74, v0
	v_mov_b32_e32 v75, v0
	s_waitcnt vmcnt(0)
	v_mov_b32_e32 v80, v0
	v_mov_b32_e32 v81, v0
	v_mov_b32_e32 v82, v0
	v_mov_b32_e32 v83, v0
	v_mov_b32_e32 v88, v0
	v_mov_b32_e32 v89, v0
	v_mov_b32_e32 v90, v0
	v_mov_b32_e32 v91, v0
	v_mov_b32_e32 v96, v0
	v_mov_b32_e32 v97, v0
	v_mov_b32_e32 v98, v0
	v_mov_b32_e32 v99, v0
	v_mov_b32_e32 v104, v0
	v_mov_b32_e32 v105, v0
	v_mov_b32_e32 v106, v0
	v_mov_b32_e32 v107, v0
	v_mov_b32_e32 v116, v0
	v_mov_b32_e32 v117, v0
	v_mov_b32_e32 v118, v0
	v_mov_b32_e32 v119, v0
	v_mov_b32_e32 v76, v0
	v_mov_b32_e32 v77, v0
	v_mov_b32_e32 v78, v0
	v_mov_b32_e32 v79, v0
	v_mov_b32_e32 v84, v0
	v_mov_b32_e32 v85, v0
	v_mov_b32_e32 v86, v0
	v_mov_b32_e32 v87, v0
	v_mov_b32_e32 v92, v0
	v_mov_b32_e32 v93, v0
	v_mov_b32_e32 v94, v0
	v_mov_b32_e32 v95, v0
	v_mov_b32_e32 v100, v0
	v_mov_b32_e32 v101, v0
	v_mov_b32_e32 v102, v0
	v_mov_b32_e32 v103, v0
	v_mov_b32_e32 v108, v0
	v_mov_b32_e32 v109, v0
	v_mov_b32_e32 v110, v0
	v_mov_b32_e32 v111, v0
	v_mov_b32_e32 v112, v0
	v_mov_b32_e32 v113, v0
	v_mov_b32_e32 v114, v0
	v_mov_b32_e32 v115, v0
	v_mov_b32_e32 v120, v0
	v_mov_b32_e32 v121, v0
	v_mov_b32_e32 v122, v0
	v_mov_b32_e32 v123, v0
	v_mov_b32_e32 v124, v0
	v_mov_b32_e32 v125, v0
	v_mov_b32_e32 v126, v0
	v_mov_b32_e32 v127, v0
	.p2align	6

; template <class Epi, class Sched, bool ALIGN_EPI = true>
; __device__ __forceinline__ void gemm_phase(LAS unsigned char* lds, const Gemm g, const Sched& S, const Epi& E, const int tid) {
;     ...
;         const bool has_next = S.next(ui + 1, nxt);
;         const char* nA = has_next ? (const char*)g.A + (size_t)nxt.pm * tstepA + (size_t)nxt.koff * 2 : cA; const char* nB = has_next ? (const char*)g.Bt + (size_t)nxt.pn * tstepB + (size_t)nxt.koff * 2 : cB;
;         const int nt = cur.nt;
;         for (int t = 0; t < nt; t += 2) {
;             const bool last = (t == nt - 2);
;             const char* a1 = cA + (size_t)(t + 1) * kstep;
;             const char* a2 = last ? nA : cA + (size_t)(t + 2) * kstep; const char* b2 = last ? nB : cB + (size_t)(t + 2) * kstep;
;     ...
; #pragma unroll
;         for (int a = 0; a < 2; ++a)
; #pragma unroll
;             for (int b = 0; b < 2; ++b)
; #pragma unroll
;                 for (int m = 0; m < 4; ++m)
; #pragma unroll
;                     for (int n = 0; n < 2; ++n) acc[a][b][m][n] = (f32x4){0.f, 0.f, 0.f, 0.f};
.LBB0_816:
	s_ashr_i32 s13, s12, 31
	s_lshl_b64 s[14:15], s[12:13], 19
	s_add_u32 s14, s9, s14
	s_addc_u32 s15, s30, s15
	s_and_b64 s[16:17], s[18:19], exec
	s_cselect_b32 s13, s15, s25
	s_cselect_b32 s48, s14, s24
	s_ashr_i32 s11, s10, 31
	s_lshl_b64 s[16:17], s[10:11], 19
	s_add_u32 s16, s31, s16
	s_addc_u32 s17, s34, s17
	s_and_b64 s[28:29], s[18:19], exec
	s_cselect_b32 s11, s17, s27
	s_cselect_b32 s49, s16, s26
	s_add_u32 s24, s24, 0x40080
	s_addc_u32 s25, s25, 0
	s_add_u32 s50, s26, 0x100
	v_mov_b32_e32 v0, 0
	v_mov_b32_e32 v133, v145
	v_mov_b32_e32 v129, v145
	v_mov_b32_e32 v131, v145
	s_addc_u32 s51, s27, 0
	s_mov_b32 s52, -2
	v_add_u32_e32 v137, 0, v8
	v_mov_b32_e32 v1, v0
	v_mov_b32_e32 v2, v0
	v_mov_b32_e32 v3, v0
	v_mov_b32_e32 v4, v0
	v_mov_b32_e32 v5, v0
	v_mov_b32_e32 v6, v0
	v_mov_b32_e32 v7, v0
	v_mov_b32_e32 v16, v0
	v_mov_b32_e32 v17, v0
	v_mov_b32_e32 v18, v0
	v_mov_b32_e32 v19, v0
	v_mov_b32_e32 v20, v0
	v_mov_b32_e32 v21, v0
	v_mov_b32_e32 v22, v0
	v_mov_b32_e32 v23, v0
	v_mov_b32_e32 v32, v0
	v_mov_b32_e32 v33, v0
	v_mov_b32_e32 v34, v0
	v_mov_b32_e32 v35, v0
	v_mov_b32_e32 v36, v0
	v_mov_b32_e32 v37, v0
	v_mov_b32_e32 v38, v0
	v_mov_b32_e32 v39, v0
	v_mov_b32_e32 v48, v0
	v_mov_b32_e32 v49, v0
	v_mov_b32_e32 v50, v0
	v_mov_b32_e32 v51, v0
	v_mov_b32_e32 v52, v0
	v_mov_b32_e32 v53, v0
	v_mov_b32_e32 v54, v0
	v_mov_b32_e32 v55, v0
	v_mov_b32_e32 v8, v0
	v_mov_b32_e32 v9, v0
	v_mov_b32_e32 v10, v0
	v_mov_b32_e32 v11, v0
	v_mov_b32_e32 v12, v0
	v_mov_b32_e32 v13, v0
	v_mov_b32_e32 v14, v0
	v_mov_b32_e32 v15, v0
	v_mov_b32_e32 v24, v0
	v_mov_b32_e32 v25, v0
	v_mov_b32_e32 v26, v0
	v_mov_b32_e32 v27, v0
	v_mov_b32_e32 v28, v0
	v_mov_b32_e32 v29, v0
	v_mov_b32_e32 v30, v0
	v_mov_b32_e32 v31, v0
	v_mov_b32_e32 v40, v0
	v_mov_b32_e32 v41, v0
	v_mov_b32_e32 v42, v0
	v_mov_b32_e32 v43, v0
	v_mov_b32_e32 v44, v0
	v_mov_b32_e32 v45, v0
	v_mov_b32_e32 v46, v0
	v_mov_b32_e32 v47, v0
	v_mov_b32_e32 v56, v0
	v_mov_b32_e32 v57, v0
	v_mov_b32_e32 v58, v0
	v_mov_b32_e32 v59, v0
	v_mov_b32_e32 v60, v0
	v_mov_b32_e32 v61, v0
	v_mov_b32_e32 v62, v0
	v_mov_b32_e32 v63, v0
	v_mov_b32_e32 v64, v0
	v_mov_b32_e32 v65, v0
	v_mov_b32_e32 v66, v0
	v_mov_b32_e32 v67, v0
	v_mov_b32_e32 v68, v0
	v_mov_b32_e32 v69, v0
	v_mov_b32_e32 v70, v0
	v_mov_b32_e32 v71, v0
	v_mov_b32_e32 v80, v0
	v_mov_b32_e32 v81, v0
	v_mov_b32_e32 v82, v0
	v_mov_b32_e32 v83, v0
	v_mov_b32_e32 v84, v0
	v_mov_b32_e32 v85, v0
	v_mov_b32_e32 v86, v0
	v_mov_b32_e32 v87, v0
	v_mov_b32_e32 v96, v0
	v_mov_b32_e32 v97, v0
	v_mov_b32_e32 v98, v0
	v_mov_b32_e32 v99, v0
	v_mov_b32_e32 v100, v0
	v_mov_b32_e32 v101, v0
	v_mov_b32_e32 v102, v0
	v_mov_b32_e32 v103, v0
	v_mov_b32_e32 v112, v0
	v_mov_b32_e32 v113, v0
	v_mov_b32_e32 v114, v0
	v_mov_b32_e32 v115, v0
	v_mov_b32_e32 v116, v0
	v_mov_b32_e32 v117, v0
	v_mov_b32_e32 v118, v0
	v_mov_b32_e32 v119, v0
	v_mov_b32_e32 v72, v0
	v_mov_b32_e32 v73, v0
	v_mov_b32_e32 v74, v0
	v_mov_b32_e32 v75, v0
	v_mov_b32_e32 v76, v0
	v_mov_b32_e32 v77, v0
	v_mov_b32_e32 v78, v0
	v_mov_b32_e32 v79, v0
	v_mov_b32_e32 v88, v0
	v_mov_b32_e32 v89, v0
	v_mov_b32_e32 v90, v0
	v_mov_b32_e32 v91, v0
	v_mov_b32_e32 v92, v0
	v_mov_b32_e32 v93, v0
	v_mov_b32_e32 v94, v0
	v_mov_b32_e32 v95, v0
	v_mov_b32_e32 v104, v0
	v_mov_b32_e32 v105, v0
	v_mov_b32_e32 v106, v0
	v_mov_b32_e32 v107, v0
	v_mov_b32_e32 v108, v0
	v_mov_b32_e32 v109, v0
	v_mov_b32_e32 v110, v0
	v_mov_b32_e32 v111, v0
	v_mov_b32_e32 v120, v0
	v_mov_b32_e32 v121, v0
	v_mov_b32_e32 v122, v0
	v_mov_b32_e32 v123, v0
	v_mov_b32_e32 v124, v0
	v_mov_b32_e32 v125, v0
	v_mov_b32_e32 v126, v0
	v_mov_b32_e32 v127, v0
	.p2align	6

; template <class Epi, class Sched, bool ALIGN_EPI = true>
; __device__ __forceinline__ void gemm_phase(LAS unsigned char* lds, const Gemm g, const Sched& S, const Epi& E, const int tid) {
;     ...
;         const int nt = cur.nt;
;         for (int t = 0; t < nt; t += 2) {
;             const bool last = (t == nt - 2);
;             const char* a1 = cA + (size_t)(t + 1) * kstep;
;             const char* a2 = last ? nA : cA + (size_t)(t + 2) * kstep; const char* b2 = last ? nB : cB + (size_t)(t + 2) * kstep;
;             const char* a3 = a2 + kstep; const char* b3 = b2 + kstep;
;     ...
; #pragma unroll
;         for (int a = 0; a < 2; ++a)
; #pragma unroll
;             for (int b = 0; b < 2; ++b)
; #pragma unroll
;                 for (int m = 0; m < 4; ++m)
; #pragma unroll
;                     for (int n = 0; n < 2; ++n) acc[a][b][m][n] = (f32x4){0.f, 0.f, 0.f, 0.f};
.LBB0_906:
	s_add_i32 s17, s55, -2
	s_add_u32 s28, s28, 0x100080
	s_addc_u32 s29, s29, 0
	s_add_u32 s19, s30, 0x100
	v_mov_b32_e32 v0, 0
	v_mov_b32_e32 v129, v145
	s_addc_u32 s21, s31, 0
	s_mov_b32 s27, 0
	v_add_u32_e32 v131, 0, v8
	v_mov_b32_e32 v1, v0
	v_mov_b32_e32 v2, v0
	v_mov_b32_e32 v3, v0
	v_mov_b32_e32 v4, v0
	v_mov_b32_e32 v5, v0
	v_mov_b32_e32 v6, v0
	v_mov_b32_e32 v7, v0
	v_mov_b32_e32 v8, v0
	v_mov_b32_e32 v9, v0
	v_mov_b32_e32 v10, v0
	v_mov_b32_e32 v11, v0
	v_mov_b32_e32 v12, v0
	v_mov_b32_e32 v13, v0
	v_mov_b32_e32 v14, v0
	v_mov_b32_e32 v15, v0
	v_mov_b32_e32 v20, v0
	v_mov_b32_e32 v21, v0
	v_mov_b32_e32 v22, v0
	v_mov_b32_e32 v23, v0
	v_mov_b32_e32 v28, v0
	v_mov_b32_e32 v29, v0
	v_mov_b32_e32 v30, v0
	v_mov_b32_e32 v31, v0
	v_mov_b32_e32 v36, v0
	v_mov_b32_e32 v37, v0
	v_mov_b32_e32 v38, v0
	v_mov_b32_e32 v39, v0
	v_mov_b32_e32 v44, v0
	v_mov_b32_e32 v45, v0
	v_mov_b32_e32 v46, v0
	v_mov_b32_e32 v47, v0
	v_mov_b32_e32 v16, v0
	v_mov_b32_e32 v17, v0
	v_mov_b32_e32 v18, v0
	v_mov_b32_e32 v19, v0
	v_mov_b32_e32 v24, v0
	v_mov_b32_e32 v25, v0
	v_mov_b32_e32 v26, v0
	v_mov_b32_e32 v27, v0
	v_mov_b32_e32 v32, v0
	v_mov_b32_e32 v33, v0
	v_mov_b32_e32 v34, v0
	v_mov_b32_e32 v35, v0
	v_mov_b32_e32 v40, v0
	v_mov_b32_e32 v41, v0
	v_mov_b32_e32 v42, v0
	v_mov_b32_e32 v43, v0
	v_mov_b32_e32 v48, v0
	v_mov_b32_e32 v49, v0
	v_mov_b32_e32 v50, v0
	v_mov_b32_e32 v51, v0
	v_mov_b32_e32 v52, v0
	v_mov_b32_e32 v53, v0
	v_mov_b32_e32 v54, v0
	v_mov_b32_e32 v55, v0
	v_mov_b32_e32 v56, v0
	v_mov_b32_e32 v57, v0
	v_mov_b32_e32 v58, v0
	v_mov_b32_e32 v59, v0
	v_mov_b32_e32 v60, v0
	v_mov_b32_e32 v61, v0
	v_mov_b32_e32 v62, v0
	v_mov_b32_e32 v63, v0
	v_mov_b32_e32 v64, v0
	v_mov_b32_e32 v65, v0
	v_mov_b32_e32 v66, v0
	v_mov_b32_e32 v67, v0
	v_mov_b32_e32 v68, v0
	v_mov_b32_e32 v69, v0
	v_mov_b32_e32 v70, v0
	v_mov_b32_e32 v71, v0
	v_mov_b32_e32 v72, v0
	v_mov_b32_e32 v73, v0
	v_mov_b32_e32 v74, v0
	v_mov_b32_e32 v75, v0
	v_mov_b32_e32 v76, v0
	v_mov_b32_e32 v77, v0
	v_mov_b32_e32 v78, v0
	v_mov_b32_e32 v79, v0
	v_mov_b32_e32 v84, v0
	v_mov_b32_e32 v85, v0
	v_mov_b32_e32 v86, v0
	v_mov_b32_e32 v87, v0
	v_mov_b32_e32 v92, v0
	v_mov_b32_e32 v93, v0
	v_mov_b32_e32 v94, v0
	v_mov_b32_e32 v95, v0
	v_mov_b32_e32 v100, v0
	v_mov_b32_e32 v101, v0
	v_mov_b32_e32 v102, v0
	v_mov_b32_e32 v103, v0
	v_mov_b32_e32 v108, v0
	v_mov_b32_e32 v109, v0
	v_mov_b32_e32 v110, v0
	v_mov_b32_e32 v111, v0
	v_mov_b32_e32 v80, v0
	v_mov_b32_e32 v81, v0
	v_mov_b32_e32 v82, v0
	v_mov_b32_e32 v83, v0
	v_mov_b32_e32 v88, v0
	v_mov_b32_e32 v89, v0
	v_mov_b32_e32 v90, v0
	v_mov_b32_e32 v91, v0
	v_mov_b32_e32 v96, v0
	v_mov_b32_e32 v97, v0
	v_mov_b32_e32 v98, v0
	v_mov_b32_e32 v99, v0
	v_mov_b32_e32 v104, v0
	v_mov_b32_e32 v105, v0
	v_mov_b32_e32 v106, v0
	v_mov_b32_e32 v107, v0
	v_mov_b32_e32 v112, v0
	v_mov_b32_e32 v113, v0
	v_mov_b32_e32 v114, v0
	v_mov_b32_e32 v115, v0
	v_mov_b32_e32 v116, v0
	v_mov_b32_e32 v117, v0
	v_mov_b32_e32 v118, v0
	v_mov_b32_e32 v119, v0
	v_mov_b32_e32 v120, v0
	v_mov_b32_e32 v121, v0
	v_mov_b32_e32 v122, v0
	v_mov_b32_e32 v123, v0
	v_mov_b32_e32 v124, v0
	v_mov_b32_e32 v125, v0
	v_mov_b32_e32 v126, v0
	v_mov_b32_e32 v127, v0
	.p2align	6
